# rwb epilogue hand-scheduled with hipcc's exact operations minus the never-taken generic-log range handling (bit-identical), w0/a0 rows staged in LDS so the loop no longer waits on vmcnt, waves 4-7 sta
# baseline (speedup 1.0000x reference)
; #define LAS __attribute__((address_space(3)))
; __device__ __forceinline__ f32x4 mfma16(h8 a, h8 b, f32x4 c) { return __builtin_amdgcn_mfma_f32_16x16x32_f16(a, b, c, 0, 0, 0); }
; __device__ __forceinline__ float sigmoidf_(float x) { return __builtin_amdgcn_rcpf(1.0f + __expf(-x)); }
; __device__ __forceinline__ float siluf_(float x) { return x * __builtin_amdgcn_rcpf(1.0f + __expf(-x)); }
; __device__ __forceinline__ float softplusf_(float x) { return x > 20.f ? x : __logf(1.0f + __expf(x)); }
; __device__ __forceinline__ void phase_rwb(const int wvs, const Params& p, LAS unsigned char* lds, int layer) {
;     ...
;     for (int nt = 0; nt < 24; ++nt) { f32x4 aw = {0.f, 0.f, 0.f, 0.f}, aa = {0.f, 0.f, 0.f, 0.f};
;       const int n4 = nt * 16 + fq * 4; const f32x4 w04 = *(const f32x4*)(w0 + n4), a04 = *(const f32x4*)(a0 + n4);
; #pragma unroll
;       for (int ks = 0; ks < 2; ++ks) { aw = mfma16(*(const LAS h8*)(lds + (nt * 16 + fr) * 144 + ks * 64 + fq * 16), bw[ks], aw); aa = mfma16(*(const LAS h8*)(lds + 55296 + (nt * 16 + fr) * 144 + ks * 64 + fq * 16), ba[ks], aa); }
;       h4 oe, oa;
; #pragma unroll
;       for (int r = 0; r < 4; ++r) { const float wl = -softplusf_(-(w04[r] + aw[r])) - 0.5f; oe[r] = (hf)__expf(wl); oa[r] = (hf)sigmoidf_(a04[r] + aa[r]); }
;       *(h4*)(P + tok * PP + PC_EF + d * 384 + n4) = oe; *(h4*)(P + tok * PP + PC_AF + d * 384 + n4) = oa; }
.Lrwb_go:
.LBB0_1146:
	ds_read_b128 v[18:21], v106
	ds_read_b128 v[22:25], v106 offset:1536
	ds_read_b128 v[34:37], v32
	ds_read_b128 v[42:45], v32 offset:64
	ds_read_b128 v[38:41], v32 offset:55296
	s_add_u32 s14, s14, 0x80
	s_addc_u32 s15, s15, 0
	s_waitcnt lgkmcnt(2)
	v_mfma_f32_16x16x32_f16 v[34:37], v[34:37], v[2:5], 0
	s_cmpk_eq_i32 s14, 0x600
	s_waitcnt lgkmcnt(1)
	v_mfma_f32_16x16x32_f16 v[34:37], v[42:45], v[10:13], v[34:37]
	ds_read_b128 v[42:45], v32 offset:55360
	s_waitcnt lgkmcnt(1)
	v_mfma_f32_16x16x32_f16 v[38:41], v[38:41], v[6:9], 0
	s_waitcnt lgkmcnt(0)
	v_mfma_f32_16x16x32_f16 v[38:41], v[42:45], v[14:17], v[38:41]
	s_nop 0
	s_nop 1
	v_add_f32_e32 v18, v18, v34
	v_add_f32_e32 v19, v19, v35
	v_add_f32_e32 v20, v20, v36
	v_add_f32_e32 v21, v21, v37
	v_mul_f32_e32 v42, 0xbfb8aa3b, v18
	v_mul_f32_e32 v43, 0xbfb8aa3b, v19
	v_mul_f32_e32 v44, 0xbfb8aa3b, v20
	v_mul_f32_e32 v45, 0xbfb8aa3b, v21
	v_exp_f32_e32 v42, v42
	v_exp_f32_e32 v43, v43
	v_exp_f32_e32 v44, v44
	v_exp_f32_e32 v45, v45
	v_add_f32_e32 v42, 1.0, v42
	v_add_f32_e32 v43, 1.0, v43
	v_add_f32_e32 v44, 1.0, v44
	v_add_f32_e32 v45, 1.0, v45
	v_log_f32_e32 v42, v42
	v_log_f32_e32 v43, v43
	v_log_f32_e32 v44, v44
	v_log_f32_e32 v45, v45
	v_add_f32_e32 v22, v22, v38
	v_add_f32_e32 v23, v23, v39
	v_add_f32_e32 v24, v24, v40
	v_add_f32_e32 v25, v25, v41
	v_mul_f32_e32 v34, 0x3f317217, v42
	v_mul_f32_e32 v35, 0x3f317217, v43
	v_mul_f32_e32 v36, 0x3f317217, v44
	v_mul_f32_e32 v37, 0x3f317217, v45
	v_fma_f32 v34, v42, s66, -v34
	v_fma_f32 v35, v43, s66, -v35
	v_fma_f32 v36, v44, s66, -v36
	v_fma_f32 v37, v45, s66, -v37
	v_fmac_f32_e32 v34, 0x3377d1cf, v42
	v_fmac_f32_e32 v35, 0x3377d1cf, v43
	v_fmac_f32_e32 v36, 0x3377d1cf, v44
	v_fmac_f32_e32 v37, 0x3377d1cf, v45
	v_fmac_f32_e32 v34, 0x3f317217, v42
	v_fmac_f32_e32 v35, 0x3f317217, v43
	v_fmac_f32_e32 v36, 0x3f317217, v44
	v_fmac_f32_e32 v37, 0x3f317217, v45
	v_mul_f32_e32 v22, 0xbfb8aa3b, v22
	v_mul_f32_e32 v23, 0xbfb8aa3b, v23
	v_mul_f32_e32 v24, 0xbfb8aa3b, v24
	v_mul_f32_e32 v25, 0xbfb8aa3b, v25
	v_cmp_gt_f32_e32 vcc, s71, v18
	v_cmp_gt_f32_e64 s[4:5], s71, v19
	v_cmp_gt_f32_e64 s[6:7], s71, v20
	v_exp_f32_e32 v22, v22
	v_cndmask_b32_e64 v18, v34, -v18, vcc
	v_cmp_gt_f32_e32 vcc, s71, v21
	v_cndmask_b32_e64 v19, v35, -v19, s[4:5]
	v_cndmask_b32_e64 v20, v36, -v20, s[6:7]
	v_exp_f32_e32 v23, v23
	v_cndmask_b32_e64 v21, v37, -v21, vcc
	v_exp_f32_e32 v24, v24
	v_exp_f32_e32 v25, v25
	v_sub_f32_e32 v18, -0.5, v18
	v_sub_f32_e32 v19, -0.5, v19
	v_sub_f32_e32 v20, -0.5, v20
	v_sub_f32_e32 v21, -0.5, v21
	v_mul_f32_e32 v18, 0x3fb8aa3b, v18
	v_mul_f32_e32 v19, 0x3fb8aa3b, v19
	v_mul_f32_e32 v20, 0x3fb8aa3b, v20
	v_mul_f32_e32 v21, 0x3fb8aa3b, v21
	v_exp_f32_e32 v18, v18
	v_exp_f32_e32 v19, v19
	v_exp_f32_e32 v20, v20
	v_exp_f32_e32 v21, v21
	v_add_f32_e32 v22, 1.0, v22
	v_add_f32_e32 v23, 1.0, v23
	v_add_f32_e32 v24, 1.0, v24
	v_add_f32_e32 v25, 1.0, v25
	v_rcp_f32_e32 v22, v22
	v_rcp_f32_e32 v23, v23
	v_rcp_f32_e32 v24, v24
	v_rcp_f32_e32 v25, v25
	s_nop 0
	v_cvt_pk_f16_f32 v18, v18, v19
	v_cvt_pk_f16_f32 v19, v20, v21
	v_cvt_pk_f16_f32 v20, v22, v23
	v_cvt_pk_f16_f32 v21, v24, v25
	global_store_dwordx2 v[26:27], v[18:19], off offset:-1536
	global_store_dwordx2 v[26:27], v[20:21], off
	ds_read_b128 v[22:25], v106 offset:64
	ds_read_b128 v[18:21], v106 offset:1600
	ds_read_b128 v[34:37], v32 offset:2304
	ds_read_b128 v[42:45], v32 offset:2368
	s_waitcnt lgkmcnt(1)
	v_mfma_f32_16x16x32_f16 v[34:37], v[34:37], v[2:5], 0
	ds_read_b128 v[38:41], v32 offset:57600
	s_waitcnt lgkmcnt(1)
	v_mfma_f32_16x16x32_f16 v[34:37], v[42:45], v[10:13], v[34:37]
	ds_read_b128 v[42:45], v32 offset:57664
	v_add_u32_e32 v32, 0x1200, v32
	s_waitcnt lgkmcnt(1)
	v_mfma_f32_16x16x32_f16 v[38:41], v[38:41], v[6:9], 0
	s_nop 0
	s_nop 2
	v_add_f32_e32 v22, v22, v34
	v_add_f32_e32 v23, v23, v35
	v_add_f32_e32 v24, v24, v36
	v_add_f32_e32 v25, v25, v37
	s_waitcnt lgkmcnt(0)
	v_mfma_f32_16x16x32_f16 v[38:41], v[42:45], v[14:17], v[38:41]
	v_mul_f32_e32 v46, 0xbfb8aa3b, v22
	v_mul_f32_e32 v47, 0xbfb8aa3b, v23
	v_mul_f32_e32 v48, 0xbfb8aa3b, v24
	v_mul_f32_e32 v49, 0xbfb8aa3b, v25
	v_exp_f32_e32 v46, v46
	v_exp_f32_e32 v47, v47
	v_exp_f32_e32 v48, v48
	v_exp_f32_e32 v49, v49
	v_add_f32_e32 v46, 1.0, v46
	v_add_f32_e32 v47, 1.0, v47
	v_add_f32_e32 v48, 1.0, v48
	v_add_f32_e32 v49, 1.0, v49
	v_log_f32_e32 v46, v46
	v_log_f32_e32 v47, v47
	v_log_f32_e32 v48, v48
	v_log_f32_e32 v49, v49
	v_add_f32_e32 v38, v18, v38
	v_add_f32_e32 v39, v19, v39
	v_add_f32_e32 v40, v20, v40
	v_add_f32_e32 v41, v21, v41
	v_mul_f32_e32 v34, 0x3f317217, v46
	v_mul_f32_e32 v35, 0x3f317217, v47
	v_mul_f32_e32 v36, 0x3f317217, v48
	v_mul_f32_e32 v37, 0x3f317217, v49
	v_fma_f32 v34, v46, s66, -v34
	v_fma_f32 v35, v47, s66, -v35
	v_fma_f32 v36, v48, s66, -v36
	v_fma_f32 v37, v49, s66, -v37
	v_fmac_f32_e32 v34, 0x3377d1cf, v46
	v_fmac_f32_e32 v35, 0x3377d1cf, v47
	v_fmac_f32_e32 v36, 0x3377d1cf, v48
	v_fmac_f32_e32 v37, 0x3377d1cf, v49
	v_fmac_f32_e32 v34, 0x3f317217, v46
	v_fmac_f32_e32 v35, 0x3f317217, v47
	v_fmac_f32_e32 v36, 0x3f317217, v48
	v_fmac_f32_e32 v37, 0x3f317217, v49
	v_mul_f32_e32 v38, 0xbfb8aa3b, v38
	v_mul_f32_e32 v39, 0xbfb8aa3b, v39
	v_mul_f32_e32 v40, 0xbfb8aa3b, v40
	v_mul_f32_e32 v41, 0xbfb8aa3b, v41
	v_cmp_gt_f32_e32 vcc, s71, v22
	v_cmp_gt_f32_e64 s[4:5], s71, v23
	v_cmp_gt_f32_e64 s[6:7], s71, v24
	v_exp_f32_e32 v38, v38
	v_cndmask_b32_e64 v22, v34, -v22, vcc
	v_cmp_gt_f32_e32 vcc, s71, v25
	v_cndmask_b32_e64 v23, v35, -v23, s[4:5]
	v_cndmask_b32_e64 v24, v36, -v24, s[6:7]
	v_exp_f32_e32 v39, v39
	v_cndmask_b32_e64 v25, v37, -v25, vcc
	v_exp_f32_e32 v40, v40
	v_exp_f32_e32 v41, v41
	v_sub_f32_e32 v22, -0.5, v22
	v_sub_f32_e32 v23, -0.5, v23
	v_sub_f32_e32 v24, -0.5, v24
	v_sub_f32_e32 v25, -0.5, v25
	v_mul_f32_e32 v22, 0x3fb8aa3b, v22
	v_mul_f32_e32 v23, 0x3fb8aa3b, v23
	v_mul_f32_e32 v24, 0x3fb8aa3b, v24
	v_mul_f32_e32 v25, 0x3fb8aa3b, v25
	v_exp_f32_e32 v22, v22
	v_exp_f32_e32 v23, v23
	v_exp_f32_e32 v24, v24
	v_exp_f32_e32 v25, v25
	v_add_f32_e32 v38, 1.0, v38
	v_add_f32_e32 v39, 1.0, v39
	v_add_f32_e32 v40, 1.0, v40
	v_add_f32_e32 v41, 1.0, v41
	v_rcp_f32_e32 v38, v38
	v_rcp_f32_e32 v39, v39
	v_rcp_f32_e32 v40, v40
	v_rcp_f32_e32 v41, v41
	s_nop 0
	v_cvt_pk_f16_f32 v18, v22, v23
	v_cvt_pk_f16_f32 v19, v24, v25
	v_cvt_pk_f16_f32 v20, v38, v39
	v_cvt_pk_f16_f32 v21, v40, v41
	global_store_dwordx2 v[26:27], v[18:19], off offset:-1504
	global_store_dwordx2 v[26:27], v[20:21], off offset:32
	v_lshl_add_u64 v[26:27], v[26:27], 0, 64
	v_add_u32_e32 v106, 0x80, v106
	s_cbranch_scc0 .LBB0_1146
	s_mov_b32 s6, 1
	s_mov_b64 s[4:5], 0
	s_and_b64 vcc, exec, s[12:13]
	s_cbranch_vccz .LBB0_1145
